# strategy 7.3 extended to the diff-QKV GEMM q/k epilogue (dwordx4 row stores via v_permlane32_swap)
# baseline (speedup 1.0000x reference)
; template <int EPI, bool RS>
; DI void gemm_epilogue(unsigned char* smem, f32x16 (&acc)[2][4], const float (&ssq)[4], int K, int m0, int nt256, const EpiArgs& ea, int wt, int wf, int r, int h) {
;     ...
;     if (sec < 2) {
;       const float* g = (sec == 0 ? ea.g0 : ea.g1) + wc * 64; const float sc = sec == 0 ? 0.125f * LOG2E : 1.f; bf16_t* ob = sec == 0 ? ea.o0 : ea.o1;
; #pragma unroll
;       for (int tb = 0; tb < 4; ++tb) {
;         const int tok = m0 + wt * 128 + tb * 32 + r; const float a = rstd[tb]; float ss = 0.f;
; #pragma unroll
;         for (int fb = 0; fb < 2; ++fb)
; #pragma unroll
;           for (int i = 0; i < 16; ++i) { const float v = acc[fb][tb][i] * a; acc[fb][tb][i] = v; ss += v * v; }
;         ss += __shfl_xor(ss, 32);
;         const float rr = rsqrtf(ss * (1.0f / 64.0f) + EPS) * sc;
.LBB0_446:
	s_andn2_b64 vcc, exec, s[2:3]
	s_cbranch_vccnz .LBB0_437
	s_cmp_lt_u32 s33, 4
	s_cselect_b64 vcc, -1, 0
	s_and_b64 s[0:1], vcc, exec
	s_cselect_b32 s2, s4, s6
	s_cselect_b32 s3, s5, s7
	s_cselect_b32 s1, s69, s47
	s_cselect_b32 s0, s68, s46
	s_add_u32 s2, s2, s10
	s_addc_u32 s3, s3, s11
	v_lshlrev_b32_e32 v216, 2, v190
	v_lshlrev_b32_e32 v214, 2, v200
	v_lshl_add_u64 v[210:211], s[2:3], 0, v[216:217]
	v_ashrrev_i32_e32 v215, 31, v214
	v_lshl_add_u64 v[200:201], v[214:215], 2, v[210:211]
	v_pk_mul_f32 v[210:211], v[108:109], v[208:209] op_sel_hi:[1,0]
	v_pk_mul_f32 v[212:213], v[110:111], v[208:209] op_sel_hi:[1,0]
	global_load_dwordx4 v[108:111], v[200:201], off
	v_pk_mul_f32 v[228:229], v[114:115], v[208:209] op_sel_hi:[1,0]
	v_pk_mul_f32 v[236:237], v[112:113], v[208:209] op_sel_hi:[1,0]
	v_pk_mul_f32 v[114:115], v[100:101], v[208:209] op_sel_hi:[1,0]
	v_pk_mul_f32 v[100:101], v[80:81], v[204:205] op_sel_hi:[1,0]
	v_pk_mul_f32 v[222:223], v[118:119], v[208:209] op_sel_hi:[1,0]
	v_pk_mul_f32 v[118:119], v[96:97], v[208:209] op_sel_hi:[1,0]
	v_pk_mul_f32 v[96:97], v[82:83], v[204:205] op_sel_hi:[1,0]
	v_mov_b32_e32 v82, v101
	v_mov_b32_e32 v83, v237
	v_mov_b32_e32 v80, v100
	v_mov_b32_e32 v81, v236
	v_pk_mul_f32 v[82:83], v[82:83], v[82:83]
	v_mov_b32_e32 v246, v96
	v_mov_b32_e32 v247, v228
	v_pk_fma_f32 v[80:81], v[80:81], v[80:81], v[82:83]
	v_pk_mul_f32 v[238:239], v[116:117], v[208:209] op_sel_hi:[1,0]
	v_pk_mul_f32 v[116:117], v[98:99], v[208:209] op_sel_hi:[1,0]
	v_pk_mul_f32 v[112:113], v[102:103], v[208:209] op_sel_hi:[1,0]
	v_pk_mul_f32 v[98:99], v[86:87], v[204:205] op_sel_hi:[1,0]
	v_pk_mul_f32 v[102:103], v[84:85], v[204:205] op_sel_hi:[1,0]
	v_pk_mul_f32 v[86:87], v[90:91], v[204:205] op_sel_hi:[1,0]
	v_mov_b32_e32 v90, v97
	v_mov_b32_e32 v91, v229
	v_pk_fma_f32 v[80:81], v[246:247], v[246:247], v[80:81]
	v_mov_b32_e32 v246, v102
	v_pk_fma_f32 v[80:81], v[90:91], v[90:91], v[80:81]
	v_mov_b32_e32 v247, v238
	v_mov_b32_e32 v248, v103
	v_mov_b32_e32 v249, v239
	v_pk_fma_f32 v[80:81], v[246:247], v[246:247], v[80:81]
	v_mov_b32_e32 v90, v98
	v_mov_b32_e32 v91, v222
	v_pk_fma_f32 v[80:81], v[248:249], v[248:249], v[80:81]
	v_pk_mul_f32 v[224:225], v[120:121], v[208:209] op_sel_hi:[1,0]
	v_pk_mul_f32 v[88:89], v[88:89], v[204:205] op_sel_hi:[1,0]
	v_pk_mul_f32 v[84:85], v[92:93], v[204:205] op_sel_hi:[1,0]
	v_mov_b32_e32 v92, v99
	v_mov_b32_e32 v93, v223
	v_pk_fma_f32 v[80:81], v[90:91], v[90:91], v[80:81]
	v_mov_b32_e32 v246, v88
	v_pk_fma_f32 v[80:81], v[92:93], v[92:93], v[80:81]
	v_mov_b32_e32 v247, v224
	v_pk_mul_f32 v[220:221], v[122:123], v[208:209] op_sel_hi:[1,0]
	v_mov_b32_e32 v248, v89
	v_mov_b32_e32 v249, v225
	v_pk_fma_f32 v[80:81], v[246:247], v[246:247], v[80:81]
	v_mov_b32_e32 v90, v86
	v_mov_b32_e32 v91, v220
	v_pk_fma_f32 v[80:81], v[248:249], v[248:249], v[80:81]
	v_pk_mul_f32 v[122:123], v[124:125], v[208:209] op_sel_hi:[1,0]
	v_mov_b32_e32 v92, v87
	v_mov_b32_e32 v93, v221
	v_pk_fma_f32 v[80:81], v[90:91], v[90:91], v[80:81]
	v_mov_b32_e32 v90, v84
	v_pk_fma_f32 v[80:81], v[92:93], v[92:93], v[80:81]
	v_mov_b32_e32 v91, v122
	v_pk_mul_f32 v[120:121], v[126:127], v[208:209] op_sel_hi:[1,0]
	v_pk_mul_f32 v[82:83], v[94:95], v[204:205] op_sel_hi:[1,0]
	v_mov_b32_e32 v94, v85
	v_mov_b32_e32 v95, v123
	v_pk_fma_f32 v[80:81], v[90:91], v[90:91], v[80:81]
	v_pk_mul_f32 v[90:91], v[66:67], v[204:205] op_sel_hi:[1,0]
	v_pk_mul_f32 v[66:67], v[68:69], v[204:205] op_sel_hi:[1,0]
	v_mov_b32_e32 v68, v82
	v_mov_b32_e32 v69, v120
	v_pk_fma_f32 v[80:81], v[94:95], v[94:95], v[80:81]
	v_pk_mul_f32 v[92:93], v[64:65], v[204:205] op_sel_hi:[1,0]
	v_mov_b32_e32 v246, v83
	v_mov_b32_e32 v247, v121
	v_pk_fma_f32 v[68:69], v[68:69], v[68:69], v[80:81]
	v_mov_b32_e32 v248, v93
	v_pk_fma_f32 v[68:69], v[246:247], v[246:247], v[68:69]
	v_mov_b32_e32 v246, v92
	v_mov_b32_e32 v247, v118
	v_mov_b32_e32 v249, v119
	v_pk_fma_f32 v[68:69], v[246:247], v[246:247], v[68:69]
	v_mov_b32_e32 v80, v90
	v_mov_b32_e32 v81, v116
	v_pk_fma_f32 v[68:69], v[248:249], v[248:249], v[68:69]
	v_mov_b32_e32 v94, v91
	v_mov_b32_e32 v95, v117
	v_pk_fma_f32 v[68:69], v[80:81], v[80:81], v[68:69]
	v_pk_mul_f32 v[64:65], v[70:71], v[204:205] op_sel_hi:[1,0]
	v_pk_fma_f32 v[68:69], v[94:95], v[94:95], v[68:69]
	v_mov_b32_e32 v80, v66
	v_mov_b32_e32 v81, v114
	v_pk_mul_f32 v[124:125], v[112:113], v[112:113]
	v_pk_mul_f32 v[70:71], v[64:65], v[64:65]
	v_mov_b32_e32 v94, v67
	v_mov_b32_e32 v95, v115
	v_pk_fma_f32 v[68:69], v[80:81], v[80:81], v[68:69]
	v_mov_b32_e32 v80, v70
	v_pk_fma_f32 v[68:69], v[94:95], v[94:95], v[68:69]
	v_mov_b32_e32 v81, v124
	v_pk_add_f32 v[68:69], v[80:81], v[68:69]
	v_mov_b32_e32 v124, v71
	v_pk_mul_f32 v[104:105], v[104:105], v[208:209] op_sel_hi:[1,0]
	v_pk_add_f32 v[68:69], v[124:125], v[68:69]
	v_pk_mul_f32 v[124:125], v[72:73], v[204:205] op_sel_hi:[1,0]
	v_pk_mul_f32 v[240:241], v[104:105], v[104:105]
	v_pk_mul_f32 v[72:73], v[124:125], v[124:125]
	v_pk_mul_f32 v[106:107], v[106:107], v[208:209] op_sel_hi:[1,0]
	v_pk_mul_f32 v[94:95], v[74:75], v[204:205] op_sel_hi:[1,0]
	v_mov_b32_e32 v74, v72
	v_mov_b32_e32 v75, v240
	v_pk_mul_f32 v[126:127], v[106:107], v[106:107]
	v_pk_mul_f32 v[70:71], v[94:95], v[94:95]
	v_pk_add_f32 v[68:69], v[74:75], v[68:69]
	v_mov_b32_e32 v240, v73
	v_pk_mul_f32 v[76:77], v[76:77], v[204:205] op_sel_hi:[1,0]
	v_pk_add_f32 v[68:69], v[240:241], v[68:69]
	v_mov_b32_e32 v72, v70
	v_mov_b32_e32 v73, v126
	v_pk_mul_f32 v[232:233], v[210:211], v[210:211]
	v_pk_mul_f32 v[242:243], v[76:77], v[76:77]
	v_pk_add_f32 v[68:69], v[72:73], v[68:69]
	v_mov_b32_e32 v126, v71
	v_pk_mul_f32 v[78:79], v[78:79], v[204:205] op_sel_hi:[1,0]
	v_pk_add_f32 v[68:69], v[126:127], v[68:69]
	v_mov_b32_e32 v70, v242
	v_mov_b32_e32 v71, v232
	v_pk_mul_f32 v[234:235], v[212:213], v[212:213]
	v_pk_mul_f32 v[244:245], v[78:79], v[78:79]
	v_pk_add_f32 v[68:69], v[70:71], v[68:69]
	v_mov_b32_e32 v232, v243
	v_pk_add_f32 v[68:69], v[232:233], v[68:69]
	v_mov_b32_e32 v70, v244
	v_mov_b32_e32 v71, v234
	v_pk_add_f32 v[68:69], v[70:71], v[68:69]
	v_mov_b32_e32 v234, v245
	v_pk_add_f32 v[70:71], v[234:235], v[68:69]
	ds_bpermute_b32 v73, v209, v71
	ds_bpermute_b32 v72, v209, v70
	v_lshlrev_b32_e32 v216, 8, v193
	v_lshl_add_u64 v[226:227], s[0:1], 0, v[216:217]
	s_mov_b32 s0, 0x358637bd
	v_mov_b32_e32 v195, 0x3e38aa3b
	s_waitcnt lgkmcnt(0)
; template <int EPI, bool RS>
; DI void gemm_epilogue(unsigned char* smem, f32x16 (&acc)[2][4], const float (&ssq)[4], int K, int m0, int nt256, const EpiArgs& ea, int wt, int wf, int r, int h) {
;     ...
;       for (int tb = 0; tb < 4; ++tb) {
;         const int tok = m0 + wt * 128 + tb * 32 + r; const float a = rstd[tb]; float ss = 0.f;
; #pragma unroll
;         for (int fb = 0; fb < 2; ++fb)
; #pragma unroll
;           for (int i = 0; i < 16; ++i) { const float v = acc[fb][tb][i] * a; acc[fb][tb][i] = v; ss += v * v; }
;         ss += __shfl_xor(ss, 32);
;         const float rr = rsqrtf(ss * (1.0f / 64.0f) + EPS) * sc;
;         bf16_t* op = ob + (size_t)tok * 1024 + head * 128 + wc * 64;
; #pragma unroll
;         for (int fb = 0; fb < 2; ++fb)
; #pragma unroll
;           for (int g4 = 0; g4 < 4; ++g4) {
;             const int d = fb * 32 + g4 * 8 + 4 * h;
;             const f32x4 gg = *(const f32x4*)(g + d);
;             u32x2 w; w[0] = pk2(acc[fb][tb][4 * g4] * rr * gg[0], acc[fb][tb][4 * g4 + 1] * rr * gg[1]); w[1] = pk2(acc[fb][tb][4 * g4 + 2] * rr * gg[2], acc[fb][tb][4 * g4 + 3] * rr * gg[3]);
;             *(u32x2*)(op + d) = w;
;           }
;       }
	v_pk_add_f32 v[70:71], v[70:71], v[72:73]
	v_mov_b64_e32 v[72:73], s[0:1]
	s_mov_b32 s0, 0x3c800000
	v_pk_fma_f32 v[80:81], v[70:71], s[0:1], v[72:73] op_sel_hi:[1,0,0]
	v_cndmask_b32_e32 v230, 1.0, v195, vcc
	v_mul_f32_e32 v70, 0x4b800000, v81
	v_cmp_gt_f32_e32 vcc, s67, v81
	v_ashrrev_i32_e32 v207, 31, v206
	v_lshlrev_b32_e32 v216, 1, v190
	v_cndmask_b32_e32 v70, v81, v70, vcc
	v_rsq_f32_e32 v81, v70
	v_lshlrev_b64 v[74:75], 11, v[206:207]
	v_lshl_add_u64 v[68:69], v[226:227], 0, v[216:217]
	v_lshl_add_u64 v[74:75], v[68:69], 0, v[74:75]
	v_mul_f32_e32 v126, 0x45800000, v81
	v_cndmask_b32_e32 v81, v81, v126, vcc
	v_mul_f32_e32 v126, v230, v81
	v_pk_mul_f32 v[206:207], v[236:237], v[126:127] op_sel_hi:[1,0]
	v_lshlrev_b64 v[70:71], 1, v[214:215]
	s_waitcnt vmcnt(0)
	v_pk_mul_f32 v[108:109], v[108:109], v[206:207]
	v_pk_mul_f32 v[206:207], v[228:229], v[126:127] op_sel_hi:[1,0]
	v_lshl_add_u64 v[74:75], v[74:75], 0, v[70:71]
	v_pk_mul_f32 v[110:111], v[110:111], v[206:207]
	v_cvt_pk_bf16_f32 v240, v108, v109
	v_cvt_pk_bf16_f32 v241, v110, v111
	v_bfe_u32 v248, v219, 5, 1
	v_lshlrev_b32_e32 v248, 3, v248
	v_mov_b32_e32 v249, v217
	v_lshl_add_u64 v[244:245], v[74:75], 0, v[248:249]
	global_load_dwordx4 v[108:111], v[200:201], off offset:32
	v_pk_mul_f32 v[206:207], v[238:239], v[126:127] op_sel_hi:[1,0]
	v_pk_mul_f32 v[214:215], v[220:221], v[126:127] op_sel_hi:[1,0]
	v_pk_mul_f32 v[122:123], v[122:123], v[126:127] op_sel_hi:[1,0]
	v_pk_mul_f32 v[120:121], v[120:121], v[126:127] op_sel_hi:[1,0]
	v_pk_mul_f32 v[118:119], v[118:119], v[126:127] op_sel_hi:[1,0]
	v_pk_mul_f32 v[116:117], v[116:117], v[126:127] op_sel_hi:[1,0]
	v_pk_mul_f32 v[114:115], v[114:115], v[126:127] op_sel_hi:[1,0]
	v_pk_mul_f32 v[112:113], v[112:113], v[126:127] op_sel_hi:[1,0]
	v_pk_mul_f32 v[104:105], v[104:105], v[126:127] op_sel_hi:[1,0]
	v_pk_mul_f32 v[106:107], v[106:107], v[126:127] op_sel_hi:[1,0]
	v_cmp_gt_f32_e32 vcc, s67, v80
	v_ashrrev_i32_e32 v203, 31, v202
	v_pk_mul_f32 v[44:45], v[44:45], v[198:199] op_sel_hi:[1,0]
	v_pk_mul_f32 v[46:47], v[46:47], v[198:199] op_sel_hi:[1,0]
	v_pk_mul_f32 v[42:43], v[42:43], v[198:199] op_sel_hi:[1,0]
	v_pk_mul_f32 v[40:41], v[40:41], v[198:199] op_sel_hi:[1,0]
	v_pk_mul_f32 v[12:13], v[12:13], v[196:197] op_sel_hi:[1,0]
	v_pk_mul_f32 v[14:15], v[14:15], v[196:197] op_sel_hi:[1,0]
	v_ashrrev_i32_e32 v195, 31, v194
	v_ashrrev_i32_e32 v193, 31, v192
	v_mov_b32_e32 v246, 0x358637bd
	s_waitcnt vmcnt(0)
	v_pk_mul_f32 v[108:109], v[108:109], v[206:207]
	v_pk_mul_f32 v[206:207], v[222:223], v[126:127] op_sel_hi:[1,0]
	v_cvt_pk_bf16_f32 v242, v108, v109
	v_pk_mul_f32 v[110:111], v[110:111], v[206:207]
	v_pk_mul_f32 v[206:207], v[224:225], v[126:127] op_sel_hi:[1,0]
	v_cvt_pk_bf16_f32 v243, v110, v111
	s_nop 1
	v_permlane32_swap_b32_e32 v240, v242
	v_permlane32_swap_b32_e32 v241, v243
	global_store_dwordx4 v[244:245], v[240:243], off
	global_load_dwordx4 v[108:111], v[200:201], off offset:64
	s_waitcnt vmcnt(0)
	v_pk_mul_f32 v[108:109], v[108:109], v[206:207]
	v_pk_mul_f32 v[110:111], v[110:111], v[214:215]
	v_cvt_pk_bf16_f32 v240, v108, v109
	v_cvt_pk_bf16_f32 v241, v110, v111
	s_nop 0
	global_load_dwordx4 v[108:111], v[200:201], off offset:96
	s_waitcnt vmcnt(0)
	v_pk_mul_f32 v[108:109], v[108:109], v[122:123]
	v_pk_mul_f32 v[110:111], v[110:111], v[120:121]
	v_cvt_pk_bf16_f32 v242, v108, v109
	v_cvt_pk_bf16_f32 v243, v110, v111
	s_nop 1
	v_permlane32_swap_b32_e32 v240, v242
	v_permlane32_swap_b32_e32 v241, v243
	global_store_dwordx4 v[244:245], v[240:243], off offset:32
	global_load_dwordx4 v[108:111], v[200:201], off offset:128
	s_waitcnt vmcnt(0)
	v_pk_mul_f32 v[108:109], v[108:109], v[118:119]
	v_pk_mul_f32 v[110:111], v[110:111], v[116:117]
	v_cvt_pk_bf16_f32 v240, v108, v109
	v_cvt_pk_bf16_f32 v241, v110, v111
	s_nop 0
	global_load_dwordx4 v[108:111], v[200:201], off offset:160
	s_waitcnt vmcnt(0)
	v_pk_mul_f32 v[108:109], v[114:115], v[108:109]
	v_pk_mul_f32 v[110:111], v[112:113], v[110:111]
	v_cvt_pk_bf16_f32 v242, v108, v109
	v_cvt_pk_bf16_f32 v243, v110, v111
	s_nop 1
	v_permlane32_swap_b32_e32 v240, v242
	v_permlane32_swap_b32_e32 v241, v243
	global_store_dwordx4 v[244:245], v[240:243], off offset:64
	global_load_dwordx4 v[108:111], v[200:201], off offset:192
	s_waitcnt vmcnt(0)
	v_pk_mul_f32 v[104:105], v[104:105], v[108:109]
	v_pk_mul_f32 v[106:107], v[106:107], v[110:111]
	v_cvt_pk_bf16_f32 v240, v104, v105
	v_cvt_pk_bf16_f32 v241, v106, v107
	s_nop 0
	global_load_dwordx4 v[104:107], v[200:201], off offset:224
	v_pk_mul_f32 v[108:109], v[210:211], v[126:127] op_sel_hi:[1,0]
	v_pk_mul_f32 v[110:111], v[212:213], v[126:127] op_sel_hi:[1,0]
	s_waitcnt vmcnt(0)
	v_pk_mul_f32 v[104:105], v[108:109], v[104:105]
	v_pk_mul_f32 v[106:107], v[110:111], v[106:107]
	v_cvt_pk_bf16_f32 v242, v104, v105
	v_cvt_pk_bf16_f32 v243, v106, v107
	s_nop 1
	v_permlane32_swap_b32_e32 v240, v242
	v_permlane32_swap_b32_e32 v241, v243
	global_store_dwordx4 v[244:245], v[240:243], off offset:96
	global_load_dwordx4 v[104:107], v[200:201], off
	v_mul_f32_e32 v74, 0x4b800000, v80
	v_cndmask_b32_e32 v74, v80, v74, vcc
	v_rsq_f32_e32 v80, v74
	v_lshlrev_b64 v[74:75], 11, v[202:203]
	v_lshl_add_u64 v[74:75], v[68:69], 0, v[74:75]
	v_lshl_add_u64 v[74:75], v[74:75], 0, v[70:71]
	v_mul_f32_e32 v81, 0x45800000, v80
	v_cndmask_b32_e32 v80, v80, v81, vcc
	v_mul_f32_e32 v80, v230, v80
	v_pk_mul_f32 v[100:101], v[100:101], v[80:81] op_sel_hi:[1,0]
	v_pk_mul_f32 v[96:97], v[96:97], v[80:81] op_sel_hi:[1,0]
	v_pk_mul_f32 v[98:99], v[98:99], v[80:81] op_sel_hi:[1,0]
	v_pk_mul_f32 v[88:89], v[88:89], v[80:81] op_sel_hi:[1,0]
	v_pk_mul_f32 v[86:87], v[86:87], v[80:81] op_sel_hi:[1,0]
	v_pk_mul_f32 v[84:85], v[84:85], v[80:81] op_sel_hi:[1,0]
	v_pk_mul_f32 v[82:83], v[82:83], v[80:81] op_sel_hi:[1,0]
	v_pk_mul_f32 v[66:67], v[66:67], v[80:81] op_sel_hi:[1,0]
	v_pk_mul_f32 v[64:65], v[64:65], v[80:81] op_sel_hi:[1,0]
	s_waitcnt vmcnt(0)
; template <int EPI, bool RS>
; DI void gemm_epilogue(unsigned char* smem, f32x16 (&acc)[2][4], const float (&ssq)[4], int K, int m0, int nt256, const EpiArgs& ea, int wt, int wf, int r, int h) {
;     ...
;       for (int tb = 0; tb < 4; ++tb) {
;         const int tok = m0 + wt * 128 + tb * 32 + r; const float a = rstd[tb]; float ss = 0.f;
; #pragma unroll
;         for (int fb = 0; fb < 2; ++fb)
; #pragma unroll
;           for (int i = 0; i < 16; ++i) { const float v = acc[fb][tb][i] * a; acc[fb][tb][i] = v; ss += v * v; }
;         ss += __shfl_xor(ss, 32);
;         const float rr = rsqrtf(ss * (1.0f / 64.0f) + EPS) * sc;
;         bf16_t* op = ob + (size_t)tok * 1024 + head * 128 + wc * 64;
; #pragma unroll
;         for (int fb = 0; fb < 2; ++fb)
; #pragma unroll
;           for (int g4 = 0; g4 < 4; ++g4) {
;             const int d = fb * 32 + g4 * 8 + 4 * h;
;             const f32x4 gg = *(const f32x4*)(g + d);
;             u32x2 w; w[0] = pk2(acc[fb][tb][4 * g4] * rr * gg[0], acc[fb][tb][4 * g4 + 1] * rr * gg[1]); w[1] = pk2(acc[fb][tb][4 * g4 + 2] * rr * gg[2], acc[fb][tb][4 * g4 + 3] * rr * gg[3]);
;             *(u32x2*)(op + d) = w;
;           }
;       }
	v_pk_mul_f32 v[100:101], v[104:105], v[100:101]
	v_pk_mul_f32 v[96:97], v[106:107], v[96:97]
	v_cvt_pk_bf16_f32 v240, v100, v101
	v_cvt_pk_bf16_f32 v241, v96, v97
	v_bfe_u32 v248, v219, 5, 1
	v_lshlrev_b32_e32 v248, 3, v248
	v_mov_b32_e32 v249, v217
	v_lshl_add_u64 v[244:245], v[74:75], 0, v[248:249]
	global_load_dwordx4 v[104:107], v[200:201], off offset:32
	v_pk_mul_f32 v[96:97], v[102:103], v[80:81] op_sel_hi:[1,0]
	s_waitcnt vmcnt(0)
	v_pk_mul_f32 v[98:99], v[106:107], v[98:99]
	v_pk_mul_f32 v[96:97], v[104:105], v[96:97]
	s_nop 0
	v_cvt_pk_bf16_f32 v242, v96, v97
	v_cvt_pk_bf16_f32 v243, v98, v99
	s_nop 1
	v_permlane32_swap_b32_e32 v240, v242
	v_permlane32_swap_b32_e32 v241, v243
	global_store_dwordx4 v[244:245], v[240:243], off
	global_load_dwordx4 v[96:99], v[200:201], off offset:64
	s_waitcnt vmcnt(0)
	v_pk_mul_f32 v[88:89], v[96:97], v[88:89]
	v_pk_mul_f32 v[86:87], v[98:99], v[86:87]
	v_cvt_pk_bf16_f32 v240, v88, v89
	v_cvt_pk_bf16_f32 v241, v86, v87
	s_nop 0
	global_load_dwordx4 v[86:89], v[200:201], off offset:96
	v_pk_mul_f32 v[96:97], v[12:13], v[12:13]
	v_pk_mul_f32 v[98:99], v[14:15], v[14:15]
	s_waitcnt vmcnt(0)
	v_pk_mul_f32 v[84:85], v[86:87], v[84:85]
	v_pk_mul_f32 v[82:83], v[88:89], v[82:83]
	v_cvt_pk_bf16_f32 v242, v84, v85
	v_cvt_pk_bf16_f32 v243, v82, v83
	s_nop 1
	v_permlane32_swap_b32_e32 v240, v242
	v_permlane32_swap_b32_e32 v241, v243
	global_store_dwordx4 v[244:245], v[240:243], off offset:32
	global_load_dwordx4 v[82:85], v[200:201], off offset:128
	v_pk_mul_f32 v[86:87], v[92:93], v[80:81] op_sel_hi:[1,0]
	v_pk_mul_f32 v[88:89], v[90:91], v[80:81] op_sel_hi:[1,0]
	v_pk_mul_f32 v[92:93], v[48:49], v[198:199] op_sel_hi:[1,0]
	v_pk_mul_f32 v[90:91], v[52:53], v[198:199] op_sel_hi:[1,0]
	v_pk_mul_f32 v[52:53], v[34:35], v[198:199] op_sel_hi:[1,0]
	v_pk_mul_f32 v[48:49], v[38:39], v[198:199] op_sel_hi:[1,0]
	v_pk_mul_f32 v[34:35], v[22:23], v[196:197] op_sel_hi:[1,0]
	v_pk_mul_f32 v[38:39], v[20:21], v[196:197] op_sel_hi:[1,0]
	v_pk_mul_f32 v[20:21], v[26:27], v[196:197] op_sel_hi:[1,0]
	v_pk_mul_f32 v[22:23], v[24:25], v[196:197] op_sel_hi:[1,0]
	v_pk_mul_f32 v[24:25], v[2:3], v[196:197] op_sel_hi:[1,0]
	v_pk_mul_f32 v[26:27], v[0:1], v[196:197] op_sel_hi:[1,0]
	v_pk_mul_f32 v[0:1], v[6:7], v[196:197] op_sel_hi:[1,0]
	v_pk_mul_f32 v[2:3], v[4:5], v[196:197] op_sel_hi:[1,0]
	v_pk_mul_f32 v[4:5], v[10:11], v[196:197] op_sel_hi:[1,0]
	v_pk_mul_f32 v[6:7], v[8:9], v[196:197] op_sel_hi:[1,0]
	v_pk_mul_f32 v[8:9], v[76:77], v[80:81] op_sel_hi:[1,0]
	v_pk_mul_f32 v[10:11], v[78:79], v[80:81] op_sel_hi:[1,0]
	v_mov_b32_e32 v105, v93
	v_mov_b32_e32 v103, v92
	v_pk_mul_f32 v[202:203], v[0:1], v[0:1]
	v_pk_mul_f32 v[214:215], v[6:7], v[6:7]
	v_mov_b32_e32 v220, v202
	v_mov_b32_e32 v202, v214
	v_mov_b32_e32 v114, v38
	v_mov_b32_e32 v115, v90
	v_mov_b32_e32 v116, v39
	v_mov_b32_e32 v117, v91
	v_mov_b32_e32 v110, v34
	v_mov_b32_e32 v112, v35
	v_mov_b32_e32 v122, v22
	v_mov_b32_e32 v118, v20
	v_mov_b32_e32 v120, v21
	v_mov_b32_e32 v212, v24
	v_mov_b32_e32 v213, v52
	v_mov_b32_e32 v76, v2
	v_mov_b32_e32 v78, v3
	s_waitcnt vmcnt(0)
	v_pk_mul_f32 v[82:83], v[82:83], v[86:87]
	v_pk_mul_f32 v[84:85], v[84:85], v[88:89]
	v_cvt_pk_bf16_f32 v240, v82, v83
	v_cvt_pk_bf16_f32 v241, v84, v85
	s_nop 0
	global_load_dwordx4 v[82:85], v[200:201], off offset:160
	v_pk_mul_f32 v[88:89], v[50:51], v[198:199] op_sel_hi:[1,0]
	v_pk_mul_f32 v[50:51], v[36:37], v[198:199] op_sel_hi:[1,0]
	v_pk_mul_f32 v[36:37], v[16:17], v[196:197] op_sel_hi:[1,0]
	v_pk_mul_f32 v[86:87], v[54:55], v[198:199] op_sel_hi:[1,0]
	v_mov_b32_e32 v104, v37
	v_pk_mul_f32 v[54:55], v[32:33], v[198:199] op_sel_hi:[1,0]
	v_pk_mul_f32 v[32:33], v[18:19], v[196:197] op_sel_hi:[1,0]
	v_pk_mul_f32 v[16:17], v[30:31], v[196:197] op_sel_hi:[1,0]
	v_pk_mul_f32 v[18:19], v[28:29], v[196:197] op_sel_hi:[1,0]
	v_pk_mul_f32 v[28:29], v[44:45], v[44:45]
	v_pk_mul_f32 v[30:31], v[46:47], v[46:47]
	v_mov_b32_e32 v102, v36
	v_pk_mul_f32 v[104:105], v[104:105], v[104:105]
	v_mov_b32_e32 v100, v32
	v_mov_b32_e32 v101, v88
	v_mov_b32_e32 v108, v33
	v_mov_b32_e32 v109, v89
	v_mov_b32_e32 v111, v86
	v_mov_b32_e32 v113, v87
	v_mov_b32_e32 v126, v18
	v_mov_b32_e32 v106, v19
	v_mov_b32_e32 v206, v16
	v_mov_b32_e32 v210, v17
	v_mov_b32_e32 v77, v50
	v_mov_b32_e32 v79, v51
	s_waitcnt vmcnt(0)
	v_pk_mul_f32 v[66:67], v[66:67], v[82:83]
	v_pk_mul_f32 v[64:65], v[64:65], v[84:85]
	v_cvt_pk_bf16_f32 v242, v66, v67
	v_cvt_pk_bf16_f32 v243, v64, v65
	s_nop 1
	v_permlane32_swap_b32_e32 v240, v242
	v_permlane32_swap_b32_e32 v241, v243
	global_store_dwordx4 v[244:245], v[240:243], off offset:64
	global_load_dwordx4 v[64:67], v[200:201], off offset:192
	v_pk_mul_f32 v[82:83], v[124:125], v[80:81] op_sel_hi:[1,0]
	v_pk_mul_f32 v[84:85], v[94:95], v[80:81] op_sel_hi:[1,0]
	v_pk_mul_f32 v[94:95], v[40:41], v[40:41]
	v_pk_mul_f32 v[80:81], v[4:5], v[4:5]
	v_mov_b32_e32 v124, v23
	v_mov_b32_e32 v214, v80
	v_mov_b32_e32 v80, v96
	v_mov_b32_e32 v96, v98
	s_waitcnt vmcnt(0)
; template <int EPI, bool RS>
; DI void gemm_epilogue(unsigned char* smem, f32x16 (&acc)[2][4], const float (&ssq)[4], int K, int m0, int nt256, const EpiArgs& ea, int wt, int wf, int r, int h) {
;     ...
;       for (int tb = 0; tb < 4; ++tb) {
;         const int tok = m0 + wt * 128 + tb * 32 + r; const float a = rstd[tb]; float ss = 0.f;
; #pragma unroll
;         for (int fb = 0; fb < 2; ++fb)
; #pragma unroll
;           for (int i = 0; i < 16; ++i) { const float v = acc[fb][tb][i] * a; acc[fb][tb][i] = v; ss += v * v; }
;         ss += __shfl_xor(ss, 32);
;         const float rr = rsqrtf(ss * (1.0f / 64.0f) + EPS) * sc;
;         bf16_t* op = ob + (size_t)tok * 1024 + head * 128 + wc * 64;
; #pragma unroll
;         for (int fb = 0; fb < 2; ++fb)
; #pragma unroll
;           for (int g4 = 0; g4 < 4; ++g4) {
;             const int d = fb * 32 + g4 * 8 + 4 * h;
;             const f32x4 gg = *(const f32x4*)(g + d);
;             u32x2 w; w[0] = pk2(acc[fb][tb][4 * g4] * rr * gg[0], acc[fb][tb][4 * g4 + 1] * rr * gg[1]); w[1] = pk2(acc[fb][tb][4 * g4 + 2] * rr * gg[2], acc[fb][tb][4 * g4 + 3] * rr * gg[3]);
;             *(u32x2*)(op + d) = w;
;           }
;       }
	v_pk_mul_f32 v[64:65], v[82:83], v[64:65]
	v_pk_mul_f32 v[66:67], v[84:85], v[66:67]
	v_cvt_pk_bf16_f32 v240, v64, v65
	v_cvt_pk_bf16_f32 v241, v66, v67
	s_nop 0
	global_load_dwordx4 v[64:67], v[200:201], off offset:224
	v_pk_mul_f32 v[82:83], v[58:59], v[198:199] op_sel_hi:[1,0]
	v_pk_mul_f32 v[84:85], v[56:57], v[198:199] op_sel_hi:[1,0]
	v_pk_mul_f32 v[56:57], v[62:63], v[198:199] op_sel_hi:[1,0]
	v_pk_mul_f32 v[58:59], v[60:61], v[198:199] op_sel_hi:[1,0]
	v_pk_mul_f32 v[60:61], v[48:49], v[48:49]
	v_pk_mul_f32 v[62:63], v[42:43], v[42:43]
	v_mov_b32_e32 v221, v60
	v_mov_b32_e32 v60, v203
	v_mov_b32_e32 v203, v94
	v_mov_b32_e32 v94, v215
	v_mov_b32_e32 v215, v62
	v_mov_b32_e32 v62, v81
	v_mov_b32_e32 v81, v28
	v_mov_b32_e32 v28, v97
	v_mov_b32_e32 v97, v30
	v_mov_b32_e32 v30, v99
	v_pk_fma_f32 v[98:99], v[102:103], v[102:103], v[104:105]
	v_mov_b32_e32 v123, v84
	v_pk_fma_f32 v[98:99], v[100:101], v[100:101], v[98:99]
	v_mov_b32_e32 v125, v85
	v_pk_fma_f32 v[98:99], v[108:109], v[108:109], v[98:99]
	v_mov_b32_e32 v119, v82
	v_pk_fma_f32 v[98:99], v[114:115], v[114:115], v[98:99]
	v_mov_b32_e32 v121, v83
	v_pk_fma_f32 v[98:99], v[116:117], v[116:117], v[98:99]
	v_mov_b32_e32 v127, v58
	v_pk_fma_f32 v[98:99], v[110:111], v[110:111], v[98:99]
	v_mov_b32_e32 v107, v59
	v_pk_fma_f32 v[98:99], v[112:113], v[112:113], v[98:99]
	v_mov_b32_e32 v207, v56
	v_pk_fma_f32 v[98:99], v[122:123], v[122:123], v[98:99]
	v_mov_b32_e32 v211, v57
	v_pk_fma_f32 v[98:99], v[124:125], v[124:125], v[98:99]
	s_waitcnt vmcnt(0)
	v_pk_mul_f32 v[8:9], v[8:9], v[64:65]
	v_pk_mul_f32 v[10:11], v[10:11], v[66:67]
	v_cvt_pk_bf16_f32 v242, v8, v9
	v_cvt_pk_bf16_f32 v243, v10, v11
	s_nop 1
	v_permlane32_swap_b32_e32 v240, v242
	v_permlane32_swap_b32_e32 v241, v243
	global_store_dwordx4 v[244:245], v[240:243], off offset:96
	global_load_dwordx4 v[8:11], v[200:201], off
	v_pk_fma_f32 v[98:99], v[118:119], v[118:119], v[98:99]
	v_mov_b32_e32 v66, v26
	v_pk_fma_f32 v[98:99], v[120:121], v[120:121], v[98:99]
	v_mov_b32_e32 v67, v54
	v_pk_fma_f32 v[98:99], v[126:127], v[126:127], v[98:99]
	v_mov_b32_e32 v74, v27
	v_pk_fma_f32 v[98:99], v[106:107], v[106:107], v[98:99]
	v_mov_b32_e32 v75, v55
	v_pk_fma_f32 v[98:99], v[206:207], v[206:207], v[98:99]
	v_mov_b32_e32 v64, v25
	v_pk_fma_f32 v[98:99], v[210:211], v[210:211], v[98:99]
	v_mov_b32_e32 v65, v53
	v_pk_fma_f32 v[66:67], v[66:67], v[66:67], v[98:99]
	s_nop 0
	v_pk_fma_f32 v[66:67], v[74:75], v[74:75], v[66:67]
	s_nop 0
	v_pk_fma_f32 v[66:67], v[212:213], v[212:213], v[66:67]
	s_nop 0
	v_pk_fma_f32 v[64:65], v[64:65], v[64:65], v[66:67]
	s_nop 0
	v_pk_fma_f32 v[64:65], v[76:77], v[76:77], v[64:65]
	s_nop 0
	v_pk_fma_f32 v[64:65], v[78:79], v[78:79], v[64:65]
	s_nop 0
	v_pk_add_f32 v[64:65], v[220:221], v[64:65]
	s_nop 0
	v_pk_add_f32 v[60:61], v[60:61], v[64:65]
	s_nop 0
	v_pk_add_f32 v[60:61], v[202:203], v[60:61]
	s_nop 0
	v_pk_add_f32 v[60:61], v[94:95], v[60:61]
	s_nop 0
	v_pk_add_f32 v[60:61], v[214:215], v[60:61]
	s_nop 0
	v_pk_add_f32 v[60:61], v[62:63], v[60:61]
	s_nop 0
	v_pk_add_f32 v[60:61], v[80:81], v[60:61]
	s_nop 0
	v_pk_add_f32 v[28:29], v[28:29], v[60:61]
	s_nop 0
	v_pk_add_f32 v[28:29], v[96:97], v[28:29]
	s_nop 0
	v_pk_add_f32 v[28:29], v[30:31], v[28:29]
	ds_bpermute_b32 v31, v209, v29
	ds_bpermute_b32 v30, v209, v28
	s_waitcnt lgkmcnt(0)
	v_pk_add_f32 v[28:29], v[28:29], v[30:31]
	s_nop 0
	v_pk_fma_f32 v[28:29], v[28:29], s[0:1], v[72:73] op_sel_hi:[1,0,0]
	s_nop 0
	v_mul_f32_e32 v30, 0x4b800000, v29
	v_cmp_gt_f32_e32 vcc, s67, v29
	s_nop 1
	v_cndmask_b32_e32 v29, v29, v30, vcc
	v_rsq_f32_e32 v29, v29
	v_lshlrev_b64 v[30:31], 11, v[194:195]
	v_lshl_add_u64 v[30:31], v[68:69], 0, v[30:31]
	v_lshl_add_u64 v[30:31], v[30:31], 0, v[70:71]
	v_mul_f32_e32 v60, 0x45800000, v29
	v_cndmask_b32_e32 v29, v29, v60, vcc
	v_mul_f32_e32 v60, v230, v29
	v_pk_mul_f32 v[62:63], v[92:93], v[60:61] op_sel_hi:[1,0]
	v_pk_mul_f32 v[64:65], v[88:89], v[60:61] op_sel_hi:[1,0]
	v_pk_mul_f32 v[58:59], v[58:59], v[60:61] op_sel_hi:[1,0]
	v_pk_mul_f32 v[56:57], v[56:57], v[60:61] op_sel_hi:[1,0]
	v_pk_mul_f32 v[54:55], v[54:55], v[60:61] op_sel_hi:[1,0]
	v_pk_mul_f32 v[52:53], v[52:53], v[60:61] op_sel_hi:[1,0]
	v_pk_mul_f32 v[50:51], v[50:51], v[60:61] op_sel_hi:[1,0]
	v_pk_mul_f32 v[48:49], v[48:49], v[60:61] op_sel_hi:[1,0]
	v_pk_mul_f32 v[40:41], v[40:41], v[60:61] op_sel_hi:[1,0]
	v_pk_mul_f32 v[42:43], v[42:43], v[60:61] op_sel_hi:[1,0]
	v_mul_f32_e32 v29, 0x4b800000, v28
	v_cmp_gt_f32_e32 vcc, s67, v28
	s_waitcnt vmcnt(0)
	v_pk_mul_f32 v[8:9], v[8:9], v[62:63]
	v_pk_mul_f32 v[10:11], v[10:11], v[64:65]
	v_cvt_pk_bf16_f32 v240, v8, v9
	v_cvt_pk_bf16_f32 v241, v10, v11
	v_bfe_u32 v248, v219, 5, 1
	v_lshlrev_b32_e32 v248, 3, v248
	v_mov_b32_e32 v249, v217
	v_lshl_add_u64 v[244:245], v[30:31], 0, v[248:249]
	global_load_dwordx4 v[8:11], v[200:201], off offset:32
	v_pk_mul_f32 v[62:63], v[90:91], v[60:61] op_sel_hi:[1,0]
	v_pk_mul_f32 v[64:65], v[86:87], v[60:61] op_sel_hi:[1,0]
	v_cndmask_b32_e32 v28, v28, v29, vcc
	s_waitcnt vmcnt(0)
	v_pk_mul_f32 v[8:9], v[8:9], v[62:63]
	v_pk_mul_f32 v[10:11], v[10:11], v[64:65]
	v_cvt_pk_bf16_f32 v242, v8, v9
	v_cvt_pk_bf16_f32 v243, v10, v11
	s_nop 1
	v_permlane32_swap_b32_e32 v240, v242
	v_permlane32_swap_b32_e32 v241, v243
	global_store_dwordx4 v[244:245], v[240:243], off
	global_load_dwordx4 v[8:11], v[200:201], off offset:64
	v_pk_mul_f32 v[62:63], v[84:85], v[60:61] op_sel_hi:[1,0]
	v_pk_mul_f32 v[64:65], v[82:83], v[60:61] op_sel_hi:[1,0]
	s_waitcnt vmcnt(0)
; template <int EPI, bool RS>
; DI void gemm_epilogue(unsigned char* smem, f32x16 (&acc)[2][4], const float (&ssq)[4], int K, int m0, int nt256, const EpiArgs& ea, int wt, int wf, int r, int h) {
;     ...
; #pragma unroll
;         for (int fb = 0; fb < 2; ++fb)
; #pragma unroll
;           for (int g4 = 0; g4 < 4; ++g4) {
;             const int d = fb * 32 + g4 * 8 + 4 * h;
;             const f32x4 gg = *(const f32x4*)(g + d);
;             u32x2 w; w[0] = pk2(acc[fb][tb][4 * g4] * rr * gg[0], acc[fb][tb][4 * g4 + 1] * rr * gg[1]); w[1] = pk2(acc[fb][tb][4 * g4 + 2] * rr * gg[2], acc[fb][tb][4 * g4 + 3] * rr * gg[3]);
;             *(u32x2*)(op + d) = w;
;           }
;       }
	v_pk_mul_f32 v[8:9], v[8:9], v[62:63]
	v_pk_mul_f32 v[10:11], v[10:11], v[64:65]
	v_cvt_pk_bf16_f32 v240, v8, v9
	v_cvt_pk_bf16_f32 v241, v10, v11
	s_nop 0
	global_load_dwordx4 v[8:11], v[200:201], off offset:96
	s_waitcnt vmcnt(0)
	v_pk_mul_f32 v[8:9], v[8:9], v[58:59]
	v_pk_mul_f32 v[10:11], v[10:11], v[56:57]
	v_cvt_pk_bf16_f32 v242, v8, v9
	v_cvt_pk_bf16_f32 v243, v10, v11
	s_nop 1
	v_permlane32_swap_b32_e32 v240, v242
	v_permlane32_swap_b32_e32 v241, v243
	global_store_dwordx4 v[244:245], v[240:243], off offset:32
	global_load_dwordx4 v[8:11], v[200:201], off offset:128
	s_waitcnt vmcnt(0)
	v_pk_mul_f32 v[8:9], v[8:9], v[54:55]
	v_pk_mul_f32 v[10:11], v[10:11], v[52:53]
	v_cvt_pk_bf16_f32 v240, v8, v9
	v_cvt_pk_bf16_f32 v241, v10, v11
	s_nop 0
	global_load_dwordx4 v[8:11], v[200:201], off offset:160
	s_waitcnt vmcnt(0)
	v_pk_mul_f32 v[8:9], v[50:51], v[8:9]
	v_pk_mul_f32 v[10:11], v[48:49], v[10:11]
	v_cvt_pk_bf16_f32 v242, v8, v9
	v_cvt_pk_bf16_f32 v243, v10, v11
	s_nop 1
	v_permlane32_swap_b32_e32 v240, v242
	v_permlane32_swap_b32_e32 v241, v243
	global_store_dwordx4 v[244:245], v[240:243], off offset:64
	global_load_dwordx4 v[8:11], v[200:201], off offset:192
	s_waitcnt vmcnt(0)
	v_pk_mul_f32 v[8:9], v[40:41], v[8:9]
	v_pk_mul_f32 v[10:11], v[42:43], v[10:11]
	v_cvt_pk_bf16_f32 v240, v8, v9
	v_cvt_pk_bf16_f32 v241, v10, v11
	s_nop 0
	global_load_dwordx4 v[8:11], v[200:201], off offset:224
	v_pk_mul_f32 v[40:41], v[44:45], v[60:61] op_sel_hi:[1,0]
	v_pk_mul_f32 v[42:43], v[46:47], v[60:61] op_sel_hi:[1,0]
	s_waitcnt vmcnt(0)
	v_pk_mul_f32 v[8:9], v[40:41], v[8:9]
	v_pk_mul_f32 v[10:11], v[42:43], v[10:11]
	v_cvt_pk_bf16_f32 v242, v8, v9
	v_cvt_pk_bf16_f32 v243, v10, v11
	s_nop 1
	v_permlane32_swap_b32_e32 v240, v242
	v_permlane32_swap_b32_e32 v241, v243
	global_store_dwordx4 v[244:245], v[240:243], off offset:96
	global_load_dwordx4 v[8:11], v[200:201], off
	v_rsq_f32_e32 v30, v28
	v_lshlrev_b64 v[28:29], 11, v[192:193]
	v_lshl_add_u64 v[28:29], v[68:69], 0, v[28:29]
	v_lshl_add_u64 v[28:29], v[28:29], 0, v[70:71]
	v_mul_f32_e32 v31, 0x45800000, v30
	v_cndmask_b32_e32 v30, v30, v31, vcc
	v_mul_f32_e32 v30, v230, v30
	v_pk_mul_f32 v[36:37], v[36:37], v[30:31] op_sel_hi:[1,0]
	v_pk_mul_f32 v[32:33], v[32:33], v[30:31] op_sel_hi:[1,0]
	v_pk_mul_f32 v[34:35], v[34:35], v[30:31] op_sel_hi:[1,0]
	v_pk_mul_f32 v[22:23], v[22:23], v[30:31] op_sel_hi:[1,0]
	v_pk_mul_f32 v[20:21], v[20:21], v[30:31] op_sel_hi:[1,0]
	v_pk_mul_f32 v[18:19], v[18:19], v[30:31] op_sel_hi:[1,0]
	v_pk_mul_f32 v[16:17], v[16:17], v[30:31] op_sel_hi:[1,0]
	v_pk_mul_f32 v[2:3], v[2:3], v[30:31] op_sel_hi:[1,0]
	v_pk_mul_f32 v[0:1], v[0:1], v[30:31] op_sel_hi:[1,0]
	v_pk_mul_f32 v[6:7], v[6:7], v[30:31] op_sel_hi:[1,0]
	v_pk_mul_f32 v[4:5], v[4:5], v[30:31] op_sel_hi:[1,0]
	s_waitcnt vmcnt(0)
	v_pk_mul_f32 v[8:9], v[8:9], v[36:37]
	v_pk_mul_f32 v[10:11], v[10:11], v[32:33]
	v_cvt_pk_bf16_f32 v240, v8, v9
	v_cvt_pk_bf16_f32 v241, v10, v11
	v_bfe_u32 v248, v219, 5, 1
	v_lshlrev_b32_e32 v248, 3, v248
	v_mov_b32_e32 v249, v217
	v_lshl_add_u64 v[244:245], v[28:29], 0, v[248:249]
	global_load_dwordx4 v[8:11], v[200:201], off offset:32
	v_pk_mul_f32 v[32:33], v[38:39], v[30:31] op_sel_hi:[1,0]
	s_waitcnt vmcnt(0)
	v_pk_mul_f32 v[10:11], v[10:11], v[34:35]
	v_pk_mul_f32 v[8:9], v[8:9], v[32:33]
	s_nop 0
	v_cvt_pk_bf16_f32 v242, v8, v9
	v_cvt_pk_bf16_f32 v243, v10, v11
	s_nop 1
	v_permlane32_swap_b32_e32 v240, v242
	v_permlane32_swap_b32_e32 v241, v243
	global_store_dwordx4 v[244:245], v[240:243], off
	global_load_dwordx4 v[8:11], v[200:201], off offset:64
	s_waitcnt vmcnt(0)
	v_pk_mul_f32 v[8:9], v[8:9], v[22:23]
	v_pk_mul_f32 v[10:11], v[10:11], v[20:21]
	v_cvt_pk_bf16_f32 v240, v8, v9
	v_cvt_pk_bf16_f32 v241, v10, v11
	s_nop 0
	global_load_dwordx4 v[8:11], v[200:201], off offset:96
	s_waitcnt vmcnt(0)
	v_pk_mul_f32 v[8:9], v[8:9], v[18:19]
	v_pk_mul_f32 v[10:11], v[10:11], v[16:17]
	v_cvt_pk_bf16_f32 v242, v8, v9
	v_cvt_pk_bf16_f32 v243, v10, v11
	s_nop 1
	v_permlane32_swap_b32_e32 v240, v242
	v_permlane32_swap_b32_e32 v241, v243
	global_store_dwordx4 v[244:245], v[240:243], off offset:32
	global_load_dwordx4 v[8:11], v[200:201], off offset:128
	v_pk_mul_f32 v[16:17], v[26:27], v[30:31] op_sel_hi:[1,0]
	v_pk_mul_f32 v[18:19], v[24:25], v[30:31] op_sel_hi:[1,0]
	s_waitcnt vmcnt(0)
	v_pk_mul_f32 v[8:9], v[8:9], v[16:17]
	v_pk_mul_f32 v[10:11], v[10:11], v[18:19]
	v_cvt_pk_bf16_f32 v240, v8, v9
	v_cvt_pk_bf16_f32 v241, v10, v11
	s_nop 0
	global_load_dwordx4 v[8:11], v[200:201], off offset:160
	s_waitcnt vmcnt(0)
	v_pk_mul_f32 v[2:3], v[2:3], v[8:9]
	v_pk_mul_f32 v[0:1], v[0:1], v[10:11]
	v_cvt_pk_bf16_f32 v242, v2, v3
	v_cvt_pk_bf16_f32 v243, v0, v1
	s_nop 1
	v_permlane32_swap_b32_e32 v240, v242
	v_permlane32_swap_b32_e32 v241, v243
	global_store_dwordx4 v[244:245], v[240:243], off offset:64
	global_load_dwordx4 v[0:3], v[200:201], off offset:192
	s_waitcnt vmcnt(0)
	v_pk_mul_f32 v[0:1], v[6:7], v[0:1]
	v_pk_mul_f32 v[2:3], v[4:5], v[2:3]
	v_cvt_pk_bf16_f32 v240, v0, v1
	v_cvt_pk_bf16_f32 v241, v2, v3
	s_nop 0
	global_load_dwordx4 v[0:3], v[200:201], off offset:224
	v_pk_mul_f32 v[4:5], v[12:13], v[30:31] op_sel_hi:[1,0]
	v_pk_mul_f32 v[6:7], v[14:15], v[30:31] op_sel_hi:[1,0]
	s_waitcnt vmcnt(0)
	v_pk_mul_f32 v[0:1], v[4:5], v[0:1]
	v_pk_mul_f32 v[2:3], v[6:7], v[2:3]
	v_cvt_pk_bf16_f32 v242, v0, v1
	v_cvt_pk_bf16_f32 v243, v2, v3
	s_nop 1
	v_permlane32_swap_b32_e32 v240, v242
	v_permlane32_swap_b32_e32 v241, v243
	global_store_dwordx4 v[244:245], v[240:243], off offset:96
	s_branch .LBB0_437
